# layer-0 down-projection residual epilogue (bf16 rows): same 16 cache-warming loads at the entry of the bf16 path
# baseline (speedup 1.0000x reference)
.LBB0_1943:
	v_lshlrev_b32_e32 v188, 12, v156
	v_lshl_add_u32 v188, v154, 1, v188
	global_load_dword v172, v188, s[50:51]
	global_load_dword v173, v188, s[50:51] offset:256
	s_add_u32 s98, s50, 0x10000
	s_addc_u32 s99, s51, 0
	global_load_dword v174, v188, s[98:99]
	global_load_dword v175, v188, s[98:99] offset:256
	s_add_u32 s98, s50, 0x20000
	s_addc_u32 s99, s51, 0
	global_load_dword v176, v188, s[98:99]
	global_load_dword v177, v188, s[98:99] offset:256
	s_add_u32 s98, s50, 0x30000
	s_addc_u32 s99, s51, 0
	global_load_dword v178, v188, s[98:99]
	global_load_dword v179, v188, s[98:99] offset:256
	s_add_u32 s98, s50, 0x80000
	s_addc_u32 s99, s51, 0
	global_load_dword v180, v188, s[98:99]
	global_load_dword v181, v188, s[98:99] offset:256
	s_add_u32 s98, s50, 0x90000
	s_addc_u32 s99, s51, 0
	global_load_dword v182, v188, s[98:99]
	global_load_dword v183, v188, s[98:99] offset:256
	s_add_u32 s98, s50, 0xa0000
	s_addc_u32 s99, s51, 0
	global_load_dword v184, v188, s[98:99]
	global_load_dword v185, v188, s[98:99] offset:256
	s_add_u32 s98, s50, 0xb0000
	s_addc_u32 s99, s51, 0
	global_load_dword v186, v188, s[98:99]
	global_load_dword v187, v188, s[98:99] offset:256
	s_mov_b64 s[0:1], -1
